# attention static priority moved from waves 4-7 to waves 0-3
# baseline (speedup 1.0000x reference)
; __device__ __forceinline__ int v_st(int k, int c) { const int kk = (k & ~0xC) | ((k & 4) << 1) | ((k & 8) >> 1); return ((kk >> 3) * 4 + (c >> 5)) * 512 + ((kk & 7) * 32 + (c & 31)) * 2; }
; __device__ __forceinline__ int v_rd_base(int lane) { return ((lane & 3) << 3) | (((lane >> 2) & 3) << 6) | (((lane >> 4) & 1) << 5) | (((lane >> 5) & 1) << 8); }
; __device__ __forceinline__ void attn_unit(const bf16* __restrict__ Qg, const bf16* __restrict__ KNg, const bf16* __restrict__ KRg, const bf16* __restrict__ Vg, bf16* __restrict__ AO, ...
;     ...
;   float mhat = 0.f, l_reg = 0; f32x16 negm = f32x16{}; asm volatile("" : "+v"(negm)); f32x16 o[4] = {}; bf16x8 qr[8]; char* QR_lds = lds + OFF_QR + wid * 4096;
;   const bf16* Qw = Qg + (row0 + q0 + wid * 32 + r32) * 768;
; #pragma unroll
;   for (int d0 = 0; d0 < 8; ++d0) qr[d0] = ld8(Qw + 128 * h + d0 * 16 + hi * 8);
;   { const bf16x8 t0 = ld8(Qw + 512 + 32 * h + hi * 8), t1 = ld8(Qw + 512 + 32 * h + 16 + hi * 8), t2 = ld8(Qw + 640 + 32 * h + hi * 8), t3 = ld8(Qw + 640 + 32 * h + 16 + hi * 8);
;     *(bf16x8*)(QR_lds + lane * 16) = t0; *(bf16x8*)(QR_lds + lane * 16 + 1024) = t1;
;     *(bf16x8*)(QR_lds + lane * 16 + 2048) = t2; *(bf16x8*)(QR_lds + lane * 16 + 3072) = t3; }
;   const int sr = tid >> 4, sc = (tid & 15) * 8, vst0 = v_st(sr, sc), vst1 = v_st(32 + sr, sc);
;   const int krow = 8 * wid + (lane & 7), kc8 = lane >> 3;
;   const int kwoff = (kc8 >> 1) * 2048 + (kc8 & 1) * 1024 + (krow >> 5) * 512 + (krow & 31) * 16;
;   const int vb0 = (int)(uintptr_t)V_lds + v_rd_base(lane);
;   const bf16* Vh = Vg + row0 * 512 + 128 * h;
;   const bf16* Kh = KNg + row0 * 512 + 128 * h;
;   const bf16* Rh = KRg + row0 * 64;
;   const unsigned kvoff = (unsigned)(sr * 512 + sc), knoff = (unsigned)(krow * 512 + kc8 * 8), kroff = (unsigned)(krow * 64 + kc8 * 8);
;   bf16x8 vs0, vs1, ks0, ks1, kr0;
;     ...
;   f32x16 pA0, pA1, pB0, pB1; float alA, alB; bf16x8 pa0, pa1, pa2, pa3;
;   const int NTt = (L + KVBLK - 1) / KVBLK, nv_last = L - (NTt - 1) * KVBLK;
;   if (wid >= 4) __builtin_amdgcn_s_setprio(1);
.LBB0_545:
	v_mov_b32_e32 v16, v183
	s_lshl_b32 s92, s4, 8
	v_readfirstlane_b32 s8, v16
	s_ashr_i32 s90, s8, 6
	s_lshl_b32 s0, s90, 12
	s_add_i32 s0, s0, 0
	s_and_b32 s91, s3, 3
	s_add_i32 s3, s0, 0x14800
	s_ashr_i32 s0, s92, 31
	s_add_u32 s1, s78, s92
	s_addc_u32 s4, s79, s0
	s_lshl_b32 s2, s90, 5
	s_ashr_i32 s5, s2, 31
	v_mov_b32_e32 v14, v1
	v_mov_b32_e32 v15, v1
	s_add_u32 s0, s2, s1
	v_and_b32_e32 v184, 31, v16
	v_mov_b32_e32 v0, v1
	v_mov_b32_e32 v2, v1
	v_mov_b32_e32 v3, v1
	v_mov_b32_e32 v4, v1
	v_mov_b32_e32 v5, v1
	v_mov_b32_e32 v6, v1
	v_mov_b32_e32 v7, v1
	v_mov_b32_e32 v8, v1
	v_mov_b32_e32 v9, v1
	v_mov_b32_e32 v10, v1
	v_mov_b32_e32 v11, v1
	v_mov_b32_e32 v12, v1
	v_mov_b32_e32 v13, v1
	v_mov_b64_e32 v[96:97], v[14:15]
	v_mov_b32_e32 v185, v1
	s_addc_u32 s1, s5, s4
	v_mov_b64_e32 v[94:95], v[12:13]
	v_mov_b64_e32 v[92:93], v[10:11]
	v_mov_b64_e32 v[90:91], v[8:9]
	v_mov_b64_e32 v[88:89], v[6:7]
	v_mov_b64_e32 v[86:87], v[4:5]
	v_mov_b64_e32 v[84:85], v[2:3]
	v_mov_b64_e32 v[82:83], v[0:1]
	v_lshl_add_u64 v[2:3], s[0:1], 0, v[184:185]
	v_mov_b64_e32 v[4:5], s[16:17]
	s_movk_i32 s4, 0x600
	v_mad_u64_u32 v[4:5], s[0:1], v2, s4, v[4:5]
	v_mov_b32_e32 v0, v5
	v_mad_u64_u32 v[2:3], s[0:1], v3, s4, v[0:1]
	v_bfe_u32 v196, v16, 5, 1
	v_mov_b32_e32 v5, v2
	s_lshl_b32 s70, s91, 8
	v_lshl_add_u64 v[2:3], v[4:5], 0, s[70:71]
	v_lshlrev_b32_e32 v188, 4, v196
	v_mov_b32_e32 v189, v1
	v_lshl_add_u64 v[14:15], v[2:3], 0, v[188:189]
	global_load_dwordx4 v[130:133], v[14:15], off
	global_load_dwordx4 v[134:137], v[14:15], off offset:32
	global_load_dwordx4 v[138:141], v[14:15], off offset:64
	global_load_dwordx4 v[142:145], v[14:15], off offset:96
	global_load_dwordx4 v[146:149], v[14:15], off offset:128
	global_load_dwordx4 v[150:153], v[14:15], off offset:160
	s_lshl_b32 s70, s91, 6
	v_lshl_add_u64 v[2:3], v[4:5], 0, s[70:71]
	v_lshl_add_u64 v[18:19], v[2:3], 0, v[188:189]
	global_load_dwordx4 v[2:5], v[18:19], off offset:1024
	global_load_dwordx4 v[6:9], v[18:19], off offset:1056
	global_load_dwordx4 v[10:13], v[18:19], off offset:1280
	s_nop 0
	global_load_dwordx4 v[18:21], v[18:19], off offset:1312
	s_nop 0
	global_load_dwordx4 v[154:157], v[14:15], off offset:192
	global_load_dwordx4 v[158:161], v[14:15], off offset:224
	v_and_b32_e32 v185, 63, v16
	v_lshlrev_b32_e32 v106, 4, v185
	s_lshl_b32 s0, s91, 7
	v_add_u32_e32 v189, s3, v106
	s_cmp_gt_i32 s90, 3
	s_waitcnt vmcnt(5)
	ds_write_b128 v189, v[2:5]
	s_waitcnt vmcnt(4)
	ds_write_b128 v189, v[6:9] offset:1024
	s_waitcnt vmcnt(3)
	ds_write_b128 v189, v[10:13] offset:2048
	s_waitcnt vmcnt(2)
	ds_write_b128 v189, v[18:21] offset:3072
	s_cbranch_scc1 .LBB0_547
	s_setprio 1

; __device__ __forceinline__ int v_st(int k, int c) { const int kk = (k & ~0xC) | ((k & 4) << 1) | ((k & 8) >> 1); return ((kk >> 3) * 4 + (c >> 5)) * 512 + ((kk & 7) * 32 + (c & 31)) * 2; }
; __device__ __forceinline__ int v_rd_base(int lane) { return ((lane & 3) << 3) | (((lane >> 2) & 3) << 6) | (((lane >> 4) & 1) << 5) | (((lane >> 5) & 1) << 8); }
; __device__ __forceinline__ void attn_unit(const bf16* __restrict__ Qg, const bf16* __restrict__ KNg, const bf16* __restrict__ KRg, const bf16* __restrict__ Vg, bf16* __restrict__ AO, ...
;     ...
;   float mhat = 0.f, l_reg = 0; f32x16 negm = f32x16{}; asm volatile("" : "+v"(negm)); f32x16 o[4] = {}; bf16x8 qr[8]; char* QR_lds = lds + OFF_QR + wid * 4096;
;   const bf16* Qw = Qg + (row0 + q0 + wid * 32 + r32) * 768;
; #pragma unroll
;   for (int d0 = 0; d0 < 8; ++d0) qr[d0] = ld8(Qw + 128 * h + d0 * 16 + hi * 8);
;   { const bf16x8 t0 = ld8(Qw + 512 + 32 * h + hi * 8), t1 = ld8(Qw + 512 + 32 * h + 16 + hi * 8), t2 = ld8(Qw + 640 + 32 * h + hi * 8), t3 = ld8(Qw + 640 + 32 * h + 16 + hi * 8);
;     *(bf16x8*)(QR_lds + lane * 16) = t0; *(bf16x8*)(QR_lds + lane * 16 + 1024) = t1;
;     *(bf16x8*)(QR_lds + lane * 16 + 2048) = t2; *(bf16x8*)(QR_lds + lane * 16 + 3072) = t3; }
;   const int sr = tid >> 4, sc = (tid & 15) * 8, vst0 = v_st(sr, sc), vst1 = v_st(32 + sr, sc);
;   const int krow = 8 * wid + (lane & 7), kc8 = lane >> 3;
;   const int kwoff = (kc8 >> 1) * 2048 + (kc8 & 1) * 1024 + (krow >> 5) * 512 + (krow & 31) * 16;
;   const int vb0 = (int)(uintptr_t)V_lds + v_rd_base(lane);
;   const bf16* Vh = Vg + row0 * 512 + 128 * h;
;   const bf16* Kh = KNg + row0 * 512 + 128 * h;
;   const bf16* Rh = KRg + row0 * 64;
;   const unsigned kvoff = (unsigned)(sr * 512 + sc), knoff = (unsigned)(krow * 512 + kc8 * 8), kroff = (unsigned)(krow * 64 + kc8 * 8);
;   bf16x8 vs0, vs1, ks0, ks1, kr0;
;     ...
;   f32x16 pA0, pA1, pB0, pB1; float alA, alB; bf16x8 pa0, pa1, pa2, pa3;
;   const int NTt = (L + KVBLK - 1) / KVBLK, nv_last = L - (NTt - 1) * KVBLK;
;   if (wid >= 4) __builtin_amdgcn_s_setprio(1);
.LBB0_1360:
	v_mov_b32_e32 v16, v183
	s_lshl_b32 s0, s4, 8
	v_readfirstlane_b32 s6, v16
	s_ashr_i32 s94, s6, 6
	s_or_b32 s93, s0, 16
	s_lshl_b32 s0, s94, 12
	s_add_i32 s0, s0, 0
	s_and_b32 s92, s3, 3
	s_add_i32 s3, s0, 0x14800
	s_add_u32 s0, s84, s93
	s_addc_u32 s1, s85, 0
	s_lshl_b32 s2, s94, 5
	s_ashr_i32 s4, s2, 31
	v_mov_b32_e32 v14, v1
	v_mov_b32_e32 v15, v1
	s_add_u32 s0, s2, s0
	v_and_b32_e32 v22, 31, v16
	v_mov_b32_e32 v0, v1
	v_mov_b32_e32 v2, v1
	v_mov_b32_e32 v3, v1
	v_mov_b32_e32 v4, v1
	v_mov_b32_e32 v5, v1
	v_mov_b32_e32 v6, v1
	v_mov_b32_e32 v7, v1
	v_mov_b32_e32 v8, v1
	v_mov_b32_e32 v9, v1
	v_mov_b32_e32 v10, v1
	v_mov_b32_e32 v11, v1
	v_mov_b32_e32 v12, v1
	v_mov_b32_e32 v13, v1
	v_mov_b64_e32 v[96:97], v[14:15]
	v_mov_b32_e32 v23, v1
	s_addc_u32 s1, s4, s1
	v_mov_b64_e32 v[94:95], v[12:13]
	v_mov_b64_e32 v[92:93], v[10:11]
	v_mov_b64_e32 v[90:91], v[8:9]
	v_mov_b64_e32 v[88:89], v[6:7]
	v_mov_b64_e32 v[86:87], v[4:5]
	v_mov_b64_e32 v[84:85], v[2:3]
	v_mov_b64_e32 v[82:83], v[0:1]
	v_lshl_add_u64 v[2:3], s[0:1], 0, v[22:23]
	v_mov_b64_e32 v[4:5], s[70:71]
	s_movk_i32 s4, 0x600
	v_mad_u64_u32 v[4:5], s[0:1], v2, s4, v[4:5]
	v_mov_b32_e32 v0, v5
	v_mad_u64_u32 v[2:3], s[0:1], v3, s4, v[0:1]
	v_bfe_u32 v199, v16, 5, 1
	v_mov_b32_e32 v5, v2
	s_lshl_b32 s78, s92, 8
	v_lshl_add_u64 v[2:3], v[4:5], 0, s[78:79]
	v_lshlrev_b32_e32 v184, 4, v199
	v_mov_b32_e32 v185, v1
	v_lshl_add_u64 v[14:15], v[2:3], 0, v[184:185]
	global_load_dwordx4 v[130:133], v[14:15], off
	global_load_dwordx4 v[134:137], v[14:15], off offset:32
	global_load_dwordx4 v[138:141], v[14:15], off offset:64
	global_load_dwordx4 v[142:145], v[14:15], off offset:96
	global_load_dwordx4 v[146:149], v[14:15], off offset:128
	global_load_dwordx4 v[150:153], v[14:15], off offset:160
	s_lshl_b32 s0, s92, 6
	s_mov_b32 s1, s79
	v_lshl_add_u64 v[2:3], v[4:5], 0, s[0:1]
	v_lshl_add_u64 v[18:19], v[2:3], 0, v[184:185]
	global_load_dwordx4 v[2:5], v[18:19], off offset:1024
	global_load_dwordx4 v[6:9], v[18:19], off offset:1056
	global_load_dwordx4 v[10:13], v[18:19], off offset:1280
	s_nop 0
	global_load_dwordx4 v[18:21], v[18:19], off offset:1312
	s_nop 0
	global_load_dwordx4 v[154:157], v[14:15], off offset:192
	global_load_dwordx4 v[158:161], v[14:15], off offset:224
	v_and_b32_e32 v185, 63, v16
	v_lshlrev_b32_e32 v106, 4, v185
	s_lshl_b32 s0, s92, 7
	v_add_u32_e32 v201, s3, v106
	s_cmp_gt_i32 s94, 3
	s_waitcnt vmcnt(5)
	ds_write_b128 v201, v[2:5]
	s_waitcnt vmcnt(4)
	ds_write_b128 v201, v[6:9] offset:1024
	s_waitcnt vmcnt(3)
	ds_write_b128 v201, v[10:13] offset:2048
	s_waitcnt vmcnt(2)
	ds_write_b128 v201, v[18:21] offset:3072
	s_cbranch_scc1 .LBB0_1362
	s_setprio 1
